# per-half barrier thinning (2 barriers per K-tile) in the first FFN_IN GEMM only
# speedup vs baseline: 1.0337x; 1.0337x over previous
.LBB0_151:
	s_ashr_i32 s27, s26, 31
	s_lshl_b64 s[42:43], s[26:27], 19
	s_add_u32 s42, s3, s42
	s_addc_u32 s43, s23, s43
	s_and_b64 s[44:45], s[4:5], exec
	s_cselect_b32 s27, s43, s49
	s_cselect_b32 s69, s42, s48
	s_ashr_i32 s25, s24, 31
	s_lshl_b64 s[44:45], s[24:25], 19
	s_add_u32 s44, s29, s44
	s_addc_u32 s45, s31, s45
	s_and_b64 s[52:53], s[4:5], exec
	s_cselect_b32 s25, s45, s51
	s_cselect_b32 s70, s44, s50
	s_add_u32 s48, s48, 0x40080
	s_addc_u32 s49, s49, 0
	s_add_u32 s71, s50, 0x100
	v_mov_b32_e32 v2, 0
	s_addc_u32 s72, s51, 0
	s_mov_b32 s73, -2
	v_mov_b32_e32 v3, v2
	v_mov_b32_e32 v4, v2
	v_mov_b32_e32 v5, v2
	v_mov_b32_e32 v14, v2
	v_mov_b32_e32 v15, v2
	v_mov_b32_e32 v16, v2
	v_mov_b32_e32 v17, v2
	v_mov_b32_e32 v22, v2
	v_mov_b32_e32 v23, v2
	v_mov_b32_e32 v24, v2
	v_mov_b32_e32 v25, v2
	v_mov_b32_e32 v30, v2
	v_mov_b32_e32 v31, v2
	v_mov_b32_e32 v32, v2
	v_mov_b32_e32 v33, v2
	v_mov_b32_e32 v38, v2
	v_mov_b32_e32 v39, v2
	v_mov_b32_e32 v40, v2
	v_mov_b32_e32 v41, v2
	v_mov_b32_e32 v46, v2
	v_mov_b32_e32 v47, v2
	v_mov_b32_e32 v48, v2
	v_mov_b32_e32 v49, v2
	v_mov_b32_e32 v54, v2
	v_mov_b32_e32 v55, v2
	v_mov_b32_e32 v56, v2
	v_mov_b32_e32 v57, v2
	v_mov_b32_e32 v62, v2
	v_mov_b32_e32 v63, v2
	v_mov_b32_e32 v64, v2
	v_mov_b32_e32 v65, v2
	v_mov_b32_e32 v6, v2
	v_mov_b32_e32 v7, v2
	v_mov_b32_e32 v8, v2
	v_mov_b32_e32 v9, v2
	v_mov_b32_e32 v10, v2
	v_mov_b32_e32 v11, v2
	v_mov_b32_e32 v12, v2
	v_mov_b32_e32 v13, v2
	v_mov_b32_e32 v18, v2
	v_mov_b32_e32 v19, v2
	v_mov_b32_e32 v20, v2
	v_mov_b32_e32 v21, v2
	v_mov_b32_e32 v26, v2
	v_mov_b32_e32 v27, v2
	v_mov_b32_e32 v28, v2
	v_mov_b32_e32 v29, v2
	v_mov_b32_e32 v34, v2
	v_mov_b32_e32 v35, v2
	v_mov_b32_e32 v36, v2
	v_mov_b32_e32 v37, v2
	v_mov_b32_e32 v42, v2
	v_mov_b32_e32 v43, v2
	v_mov_b32_e32 v44, v2
	v_mov_b32_e32 v45, v2
	v_mov_b32_e32 v50, v2
	v_mov_b32_e32 v51, v2
	v_mov_b32_e32 v52, v2
	v_mov_b32_e32 v53, v2
	v_mov_b32_e32 v58, v2
	v_mov_b32_e32 v59, v2
	v_mov_b32_e32 v60, v2
	v_mov_b32_e32 v61, v2
	v_mov_b32_e32 v70, v2
	v_mov_b32_e32 v71, v2
	v_mov_b32_e32 v72, v2
	v_mov_b32_e32 v73, v2
	v_mov_b32_e32 v78, v2
	v_mov_b32_e32 v79, v2
	v_mov_b32_e32 v80, v2
	v_mov_b32_e32 v81, v2
	v_mov_b32_e32 v86, v2
	v_mov_b32_e32 v87, v2
	v_mov_b32_e32 v88, v2
	v_mov_b32_e32 v89, v2
	v_mov_b32_e32 v94, v2
	v_mov_b32_e32 v95, v2
	v_mov_b32_e32 v96, v2
	v_mov_b32_e32 v97, v2
	v_mov_b32_e32 v102, v2
	v_mov_b32_e32 v103, v2
	v_mov_b32_e32 v104, v2
	v_mov_b32_e32 v105, v2
	v_mov_b32_e32 v110, v2
	v_mov_b32_e32 v111, v2
	v_mov_b32_e32 v112, v2
	v_mov_b32_e32 v113, v2
	v_mov_b32_e32 v122, v2
	v_mov_b32_e32 v123, v2
	v_mov_b32_e32 v124, v2
	v_mov_b32_e32 v125, v2
	v_mov_b32_e32 v126, v2
	v_mov_b32_e32 v127, v2
	v_mov_b32_e32 v128, v2
	v_mov_b32_e32 v129, v2
	v_mov_b32_e32 v66, v2
	v_mov_b32_e32 v67, v2
	v_mov_b32_e32 v68, v2
	v_mov_b32_e32 v69, v2
	v_mov_b32_e32 v74, v2
	v_mov_b32_e32 v75, v2
	v_mov_b32_e32 v76, v2
	v_mov_b32_e32 v77, v2
	v_mov_b32_e32 v82, v2
	v_mov_b32_e32 v83, v2
	v_mov_b32_e32 v84, v2
	v_mov_b32_e32 v85, v2
	v_mov_b32_e32 v90, v2
	v_mov_b32_e32 v91, v2
	v_mov_b32_e32 v92, v2
	v_mov_b32_e32 v93, v2
	v_mov_b32_e32 v98, v2
	v_mov_b32_e32 v99, v2
	v_mov_b32_e32 v100, v2
	v_mov_b32_e32 v101, v2
	v_mov_b32_e32 v106, v2
	v_mov_b32_e32 v107, v2
	v_mov_b32_e32 v108, v2
	v_mov_b32_e32 v109, v2
	v_mov_b32_e32 v114, v2
	v_mov_b32_e32 v115, v2
	v_mov_b32_e32 v116, v2
	v_mov_b32_e32 v117, v2
	v_mov_b32_e32 v118, v2
	v_mov_b32_e32 v119, v2
	v_mov_b32_e32 v120, v2
	v_mov_b32_e32 v121, v2
	s_cmp_eq_u64 s[16:17], 0
	s_cbranch_scc1 .Lhb_B_p1
.LBB0_152:
	ds_read_b128 v[160:163], v155
	ds_read_b128 v[164:167], v155 offset:1024
	ds_read_b128 v[168:171], v155 offset:2048
	ds_read_b128 v[172:175], v155 offset:3072
	ds_read_b128 v[176:179], v156
	ds_read_b128 v[180:183], v156 offset:1024
	ds_read_b128 v[184:187], v156 offset:2048
	ds_read_b128 v[188:191], v156 offset:3072
	s_add_u32 s50, s48, 0xfffc0080
	s_addc_u32 s51, s49, -1
	s_cmp_eq_u32 s73, 12
	s_cselect_b32 s53, s27, s51
	s_cselect_b32 s52, s69, s50
	s_cselect_b32 s51, s25, s72
	s_cselect_b32 s50, s70, s71
	v_lshl_add_u64 v[148:149], s[48:49], 0, v[140:141]
	s_add_i32 m0, s57, 0xc000
	ds_read_b128 v[192:195], v157
	ds_read_b128 v[196:199], v157 offset:1024
	ds_read_b128 v[200:203], v157 offset:2048
	ds_read_b128 v[204:207], v157 offset:3072
	ds_read_b128 v[208:211], v157 offset:4096
	ds_read_b128 v[212:215], v157 offset:5120
	ds_read_b128 v[216:219], v157 offset:6144
	ds_read_b128 v[220:223], v157 offset:7168
	global_load_lds_dwordx4 v[148:149], off
	v_lshl_add_u64 v[148:149], s[48:49], 0, v[142:143]
	s_add_i32 m0, s57, 0xe000
	s_nop 0
	global_load_lds_dwordx4 v[148:149], off
	s_waitcnt vmcnt(8)
	s_waitcnt lgkmcnt(0)
	s_setprio 1
	v_mfma_f32_16x16x32_bf16 v[118:121], v[160:163], v[192:195], v[118:121]
	v_mfma_f32_16x16x32_bf16 v[114:117], v[168:171], v[192:195], v[114:117]
	v_mfma_f32_16x16x32_bf16 v[106:109], v[160:163], v[200:203], v[106:109]
	v_mfma_f32_16x16x32_bf16 v[98:101], v[168:171], v[200:203], v[98:101]
	v_mfma_f32_16x16x32_bf16 v[90:93], v[160:163], v[208:211], v[90:93]
	v_mfma_f32_16x16x32_bf16 v[82:85], v[168:171], v[208:211], v[82:85]
	v_mfma_f32_16x16x32_bf16 v[74:77], v[160:163], v[216:219], v[74:77]
	v_mfma_f32_16x16x32_bf16 v[66:69], v[168:171], v[216:219], v[66:69]
	v_mfma_f32_16x16x32_bf16 v[118:121], v[164:167], v[196:199], v[118:121]
	v_mfma_f32_16x16x32_bf16 v[114:117], v[172:175], v[196:199], v[114:117]
	v_mfma_f32_16x16x32_bf16 v[106:109], v[164:167], v[204:207], v[106:109]
	v_mfma_f32_16x16x32_bf16 v[98:101], v[172:175], v[204:207], v[98:101]
	v_mfma_f32_16x16x32_bf16 v[90:93], v[164:167], v[212:215], v[90:93]
	v_mfma_f32_16x16x32_bf16 v[82:85], v[172:175], v[212:215], v[82:85]
	v_mfma_f32_16x16x32_bf16 v[74:77], v[164:167], v[220:223], v[74:77]
	v_mfma_f32_16x16x32_bf16 v[66:69], v[172:175], v[220:223], v[66:69]
	s_setprio 0
	s_setprio 1
	v_mfma_f32_16x16x32_bf16 v[126:129], v[176:179], v[192:195], v[126:129]
	v_mfma_f32_16x16x32_bf16 v[122:125], v[184:187], v[192:195], v[122:125]
	v_mfma_f32_16x16x32_bf16 v[110:113], v[176:179], v[200:203], v[110:113]
	v_mfma_f32_16x16x32_bf16 v[102:105], v[184:187], v[200:203], v[102:105]
	v_mfma_f32_16x16x32_bf16 v[94:97], v[176:179], v[208:211], v[94:97]
	v_mfma_f32_16x16x32_bf16 v[86:89], v[184:187], v[208:211], v[86:89]
	v_mfma_f32_16x16x32_bf16 v[78:81], v[176:179], v[216:219], v[78:81]
	v_mfma_f32_16x16x32_bf16 v[70:73], v[184:187], v[216:219], v[70:73]
	v_mfma_f32_16x16x32_bf16 v[126:129], v[180:183], v[196:199], v[126:129]
	v_mfma_f32_16x16x32_bf16 v[122:125], v[188:191], v[196:199], v[122:125]
	v_mfma_f32_16x16x32_bf16 v[110:113], v[180:183], v[204:207], v[110:113]
	v_mfma_f32_16x16x32_bf16 v[102:105], v[188:191], v[204:207], v[102:105]
	v_mfma_f32_16x16x32_bf16 v[94:97], v[180:183], v[212:215], v[94:97]
	v_mfma_f32_16x16x32_bf16 v[86:89], v[188:191], v[212:215], v[86:89]
	v_mfma_f32_16x16x32_bf16 v[78:81], v[180:183], v[220:223], v[78:81]
	v_mfma_f32_16x16x32_bf16 v[70:73], v[188:191], v[220:223], v[70:73]
	s_setprio 0
	s_barrier
	s_add_i32 s74, s66, s54
	v_lshl_add_u64 v[148:149], s[50:51], 0, v[134:135]
	s_mov_b32 m0, s74
	ds_read_b128 v[192:195], v157 offset:16384
	ds_read_b128 v[196:199], v157 offset:17408
	ds_read_b128 v[200:203], v157 offset:18432
	ds_read_b128 v[204:207], v157 offset:19456
	ds_read_b128 v[208:211], v157 offset:20480
	ds_read_b128 v[212:215], v157 offset:21504
	ds_read_b128 v[216:219], v157 offset:22528
	ds_read_b128 v[220:223], v157 offset:23552
	global_load_lds_dwordx4 v[148:149], off
	s_add_i32 m0, s74, 0x2000
	s_add_u32 s74, s50, 0x40000
	v_lshl_add_u64 v[224:225], s[50:51], 0, v[130:131]
	s_addc_u32 s75, s51, 0
	s_add_i32 s76, s67, s54
	global_load_lds_dwordx4 v[224:225], off
	v_lshl_add_u64 v[226:227], s[74:75], 0, v[134:135]
	s_mov_b32 m0, s76
	v_lshl_add_u64 v[228:229], s[52:53], 0, v[132:133]
	global_load_lds_dwordx4 v[226:227], off
	v_lshl_add_u64 v[226:227], s[74:75], 0, v[130:131]
	s_add_i32 m0, s76, 0x2000
	s_nop 0
	global_load_lds_dwordx4 v[226:227], off
	v_lshl_add_u64 v[226:227], s[52:53], 0, v[136:137]
	s_mov_b32 m0, s57
	s_nop 0
	global_load_lds_dwordx4 v[226:227], off
	s_mov_b32 m0, s58
	s_nop 0
	global_load_lds_dwordx4 v[228:229], off
	s_waitcnt vmcnt(8)
	s_waitcnt lgkmcnt(0)
	s_setprio 1
	v_mfma_f32_16x16x32_bf16 v[58:61], v[160:163], v[192:195], v[58:61]
	v_mfma_f32_16x16x32_bf16 v[50:53], v[168:171], v[192:195], v[50:53]
	v_mfma_f32_16x16x32_bf16 v[42:45], v[160:163], v[200:203], v[42:45]
	v_mfma_f32_16x16x32_bf16 v[34:37], v[168:171], v[200:203], v[34:37]
	v_mfma_f32_16x16x32_bf16 v[26:29], v[160:163], v[208:211], v[26:29]
	v_mfma_f32_16x16x32_bf16 v[18:21], v[168:171], v[208:211], v[18:21]
	v_mfma_f32_16x16x32_bf16 v[10:13], v[160:163], v[216:219], v[10:13]
	v_mfma_f32_16x16x32_bf16 v[6:9], v[168:171], v[216:219], v[6:9]
	v_mfma_f32_16x16x32_bf16 v[58:61], v[164:167], v[196:199], v[58:61]
	v_mfma_f32_16x16x32_bf16 v[50:53], v[172:175], v[196:199], v[50:53]
	v_mfma_f32_16x16x32_bf16 v[42:45], v[164:167], v[204:207], v[42:45]
	v_mfma_f32_16x16x32_bf16 v[34:37], v[172:175], v[204:207], v[34:37]
	v_mfma_f32_16x16x32_bf16 v[26:29], v[164:167], v[212:215], v[26:29]
	v_mfma_f32_16x16x32_bf16 v[18:21], v[172:175], v[212:215], v[18:21]
	v_mfma_f32_16x16x32_bf16 v[10:13], v[164:167], v[220:223], v[10:13]
	v_mfma_f32_16x16x32_bf16 v[6:9], v[172:175], v[220:223], v[6:9]
	s_setprio 0
	s_setprio 1
	v_mfma_f32_16x16x32_bf16 v[62:65], v[176:179], v[192:195], v[62:65]
	v_mfma_f32_16x16x32_bf16 v[54:57], v[184:187], v[192:195], v[54:57]
	v_mfma_f32_16x16x32_bf16 v[46:49], v[176:179], v[200:203], v[46:49]
	v_mfma_f32_16x16x32_bf16 v[38:41], v[184:187], v[200:203], v[38:41]
	v_mfma_f32_16x16x32_bf16 v[30:33], v[176:179], v[208:211], v[30:33]
	v_mfma_f32_16x16x32_bf16 v[22:25], v[184:187], v[208:211], v[22:25]
	v_mfma_f32_16x16x32_bf16 v[14:17], v[176:179], v[216:219], v[14:17]
	v_mfma_f32_16x16x32_bf16 v[2:5], v[184:187], v[216:219], v[2:5]
	v_mfma_f32_16x16x32_bf16 v[62:65], v[180:183], v[196:199], v[62:65]
	v_mfma_f32_16x16x32_bf16 v[54:57], v[188:191], v[196:199], v[54:57]
	v_mfma_f32_16x16x32_bf16 v[46:49], v[180:183], v[204:207], v[46:49]
	v_mfma_f32_16x16x32_bf16 v[38:41], v[188:191], v[204:207], v[38:41]
	v_mfma_f32_16x16x32_bf16 v[30:33], v[180:183], v[212:215], v[30:33]
	v_mfma_f32_16x16x32_bf16 v[22:25], v[188:191], v[212:215], v[22:25]
	v_mfma_f32_16x16x32_bf16 v[14:17], v[180:183], v[220:223], v[14:17]
	v_mfma_f32_16x16x32_bf16 v[2:5], v[188:191], v[220:223], v[2:5]
	s_setprio 0
	s_barrier
	s_add_i32 s74, 0, 0x18000
	v_add_u32_e32 v159, s74, v151
	s_add_i32 s75, 0, 0x1c000
	ds_read_b128 v[160:163], v159
	ds_read_b128 v[164:167], v159 offset:1024
	ds_read_b128 v[168:171], v159 offset:2048
	ds_read_b128 v[172:175], v159 offset:3072
	v_add_u32_e32 v159, s75, v151
	ds_read_b128 v[176:179], v159
	ds_read_b128 v[180:183], v159 offset:1024
	ds_read_b128 v[184:187], v159 offset:2048
	ds_read_b128 v[188:191], v159 offset:3072
	s_add_u32 s52, s52, 0x40000
	s_addc_u32 s53, s53, 0
	s_mov_b32 m0, s59
	v_lshl_add_u64 v[230:231], s[52:53], 0, v[136:137]
	ds_read_b128 v[192:195], v157 offset:32768
	ds_read_b128 v[196:199], v157 offset:33792
	ds_read_b128 v[200:203], v157 offset:34816
	ds_read_b128 v[204:207], v157 offset:35840
	ds_read_b128 v[208:211], v157 offset:36864
	ds_read_b128 v[212:215], v157 offset:37888
	ds_read_b128 v[216:219], v157 offset:38912
	ds_read_b128 v[220:223], v157 offset:39936
	global_load_lds_dwordx4 v[230:231], off
	v_lshl_add_u64 v[230:231], s[52:53], 0, v[132:133]
	s_mov_b32 m0, s60
	s_nop 0
	global_load_lds_dwordx4 v[230:231], off
	s_waitcnt vmcnt(8)
	s_waitcnt lgkmcnt(0)
	s_setprio 1
	v_mfma_f32_16x16x32_bf16 v[118:121], v[160:163], v[192:195], v[118:121]
	v_mfma_f32_16x16x32_bf16 v[114:117], v[168:171], v[192:195], v[114:117]
	v_mfma_f32_16x16x32_bf16 v[106:109], v[160:163], v[200:203], v[106:109]
	v_mfma_f32_16x16x32_bf16 v[98:101], v[168:171], v[200:203], v[98:101]
	v_mfma_f32_16x16x32_bf16 v[90:93], v[160:163], v[208:211], v[90:93]
	v_mfma_f32_16x16x32_bf16 v[82:85], v[168:171], v[208:211], v[82:85]
	v_mfma_f32_16x16x32_bf16 v[74:77], v[160:163], v[216:219], v[74:77]
	v_mfma_f32_16x16x32_bf16 v[66:69], v[168:171], v[216:219], v[66:69]
	v_mfma_f32_16x16x32_bf16 v[118:121], v[164:167], v[196:199], v[118:121]
	v_mfma_f32_16x16x32_bf16 v[114:117], v[172:175], v[196:199], v[114:117]
	v_mfma_f32_16x16x32_bf16 v[106:109], v[164:167], v[204:207], v[106:109]
	v_mfma_f32_16x16x32_bf16 v[98:101], v[172:175], v[204:207], v[98:101]
	v_mfma_f32_16x16x32_bf16 v[90:93], v[164:167], v[212:215], v[90:93]
	v_mfma_f32_16x16x32_bf16 v[82:85], v[172:175], v[212:215], v[82:85]
	v_mfma_f32_16x16x32_bf16 v[74:77], v[164:167], v[220:223], v[74:77]
	v_mfma_f32_16x16x32_bf16 v[66:69], v[172:175], v[220:223], v[66:69]
	s_setprio 0
	s_setprio 1
	v_mfma_f32_16x16x32_bf16 v[126:129], v[176:179], v[192:195], v[126:129]
	v_mfma_f32_16x16x32_bf16 v[122:125], v[184:187], v[192:195], v[122:125]
	v_mfma_f32_16x16x32_bf16 v[110:113], v[176:179], v[200:203], v[110:113]
	v_mfma_f32_16x16x32_bf16 v[102:105], v[184:187], v[200:203], v[102:105]
	v_mfma_f32_16x16x32_bf16 v[94:97], v[176:179], v[208:211], v[94:97]
	v_mfma_f32_16x16x32_bf16 v[86:89], v[184:187], v[208:211], v[86:89]
	v_mfma_f32_16x16x32_bf16 v[78:81], v[176:179], v[216:219], v[78:81]
	v_mfma_f32_16x16x32_bf16 v[70:73], v[184:187], v[216:219], v[70:73]
	v_mfma_f32_16x16x32_bf16 v[126:129], v[180:183], v[196:199], v[126:129]
	v_mfma_f32_16x16x32_bf16 v[122:125], v[188:191], v[196:199], v[122:125]
	v_mfma_f32_16x16x32_bf16 v[110:113], v[180:183], v[204:207], v[110:113]
	v_mfma_f32_16x16x32_bf16 v[102:105], v[188:191], v[204:207], v[102:105]
	v_mfma_f32_16x16x32_bf16 v[94:97], v[180:183], v[212:215], v[94:97]
	v_mfma_f32_16x16x32_bf16 v[86:89], v[188:191], v[212:215], v[86:89]
	v_mfma_f32_16x16x32_bf16 v[78:81], v[180:183], v[220:223], v[78:81]
	v_mfma_f32_16x16x32_bf16 v[70:73], v[188:191], v[220:223], v[70:73]
	s_setprio 0
	s_barrier
	s_add_i32 s52, s74, s54
	v_lshl_add_u64 v[148:149], v[148:149], 0, s[14:15]
	s_mov_b32 m0, s52
	ds_read_b128 v[192:195], v157 offset:49152
	ds_read_b128 v[196:199], v157 offset:50176
	ds_read_b128 v[200:203], v157 offset:51200
	ds_read_b128 v[204:207], v157 offset:52224
	ds_read_b128 v[208:211], v157 offset:53248
	ds_read_b128 v[212:215], v157 offset:54272
	ds_read_b128 v[216:219], v157 offset:55296
	ds_read_b128 v[220:223], v157 offset:56320
	global_load_lds_dwordx4 v[148:149], off
	s_add_i32 m0, s52, 0x2000
	s_add_u32 s50, s50, 0x40080
	v_lshl_add_u64 v[148:149], v[224:225], 0, s[14:15]
	s_addc_u32 s51, s51, 0
	s_add_i32 s52, s75, s54
	global_load_lds_dwordx4 v[148:149], off
	v_lshl_add_u64 v[148:149], s[50:51], 0, v[134:135]
	s_mov_b32 m0, s52
	s_nop 0
	global_load_lds_dwordx4 v[148:149], off
	v_lshl_add_u64 v[148:149], s[50:51], 0, v[130:131]
	s_add_i32 m0, s52, 0x2000
	s_nop 0
	global_load_lds_dwordx4 v[148:149], off
	v_lshl_add_u64 v[148:149], v[226:227], 0, s[14:15]
	s_mov_b32 m0, s62
	s_nop 0
	global_load_lds_dwordx4 v[148:149], off
	v_lshl_add_u64 v[148:149], v[228:229], 0, s[14:15]
	s_mov_b32 m0, s63
	s_nop 0
	global_load_lds_dwordx4 v[148:149], off
	s_waitcnt vmcnt(8)
	s_waitcnt lgkmcnt(0)
	s_setprio 1
	v_mfma_f32_16x16x32_bf16 v[58:61], v[160:163], v[192:195], v[58:61]
	v_mfma_f32_16x16x32_bf16 v[50:53], v[168:171], v[192:195], v[50:53]
	v_mfma_f32_16x16x32_bf16 v[42:45], v[160:163], v[200:203], v[42:45]
	v_mfma_f32_16x16x32_bf16 v[34:37], v[168:171], v[200:203], v[34:37]
	v_mfma_f32_16x16x32_bf16 v[26:29], v[160:163], v[208:211], v[26:29]
	v_mfma_f32_16x16x32_bf16 v[18:21], v[168:171], v[208:211], v[18:21]
	v_mfma_f32_16x16x32_bf16 v[10:13], v[160:163], v[216:219], v[10:13]
	v_mfma_f32_16x16x32_bf16 v[6:9], v[168:171], v[216:219], v[6:9]
	v_mfma_f32_16x16x32_bf16 v[58:61], v[164:167], v[196:199], v[58:61]
	v_mfma_f32_16x16x32_bf16 v[50:53], v[172:175], v[196:199], v[50:53]
	v_mfma_f32_16x16x32_bf16 v[42:45], v[164:167], v[204:207], v[42:45]
	v_mfma_f32_16x16x32_bf16 v[34:37], v[172:175], v[204:207], v[34:37]
	v_mfma_f32_16x16x32_bf16 v[26:29], v[164:167], v[212:215], v[26:29]
	v_mfma_f32_16x16x32_bf16 v[18:21], v[172:175], v[212:215], v[18:21]
	v_mfma_f32_16x16x32_bf16 v[10:13], v[164:167], v[220:223], v[10:13]
	v_mfma_f32_16x16x32_bf16 v[6:9], v[172:175], v[220:223], v[6:9]
	s_setprio 0
	s_setprio 1
	v_mfma_f32_16x16x32_bf16 v[62:65], v[176:179], v[192:195], v[62:65]
	v_mfma_f32_16x16x32_bf16 v[54:57], v[184:187], v[192:195], v[54:57]
	v_mfma_f32_16x16x32_bf16 v[46:49], v[176:179], v[200:203], v[46:49]
	v_mfma_f32_16x16x32_bf16 v[38:41], v[184:187], v[200:203], v[38:41]
	v_mfma_f32_16x16x32_bf16 v[30:33], v[176:179], v[208:211], v[30:33]
	v_mfma_f32_16x16x32_bf16 v[22:25], v[184:187], v[208:211], v[22:25]
	v_mfma_f32_16x16x32_bf16 v[14:17], v[176:179], v[216:219], v[14:17]
	v_mfma_f32_16x16x32_bf16 v[2:5], v[184:187], v[216:219], v[2:5]
	v_mfma_f32_16x16x32_bf16 v[62:65], v[180:183], v[196:199], v[62:65]
	v_mfma_f32_16x16x32_bf16 v[54:57], v[188:191], v[196:199], v[54:57]
	v_mfma_f32_16x16x32_bf16 v[46:49], v[180:183], v[204:207], v[46:49]
	v_mfma_f32_16x16x32_bf16 v[38:41], v[188:191], v[204:207], v[38:41]
	v_mfma_f32_16x16x32_bf16 v[30:33], v[180:183], v[212:215], v[30:33]
	v_mfma_f32_16x16x32_bf16 v[22:25], v[188:191], v[212:215], v[22:25]
	v_mfma_f32_16x16x32_bf16 v[14:17], v[180:183], v[220:223], v[14:17]
	v_mfma_f32_16x16x32_bf16 v[2:5], v[188:191], v[220:223], v[2:5]
	s_setprio 0
	s_barrier
	s_add_i32 s73, s73, 2
	s_add_u32 s48, s48, 0x100
	s_addc_u32 s49, s49, 0
	s_add_u32 s71, s71, 0x100
	s_addc_u32 s72, s72, 0
	s_cmp_gt_u32 s73, 13
	s_cbranch_scc0 .LBB0_152
	s_branch .Lhb_exit_p1
.Lhb_B_p1:
	ds_read_b128 v[160:163], v155
	ds_read_b128 v[164:167], v155 offset:1024
	ds_read_b128 v[168:171], v155 offset:2048
	ds_read_b128 v[172:175], v155 offset:3072
	ds_read_b128 v[176:179], v156
	ds_read_b128 v[180:183], v156 offset:1024
	ds_read_b128 v[184:187], v156 offset:2048
	ds_read_b128 v[188:191], v156 offset:3072
	s_add_u32 s50, s48, 0xfffc0080
	s_addc_u32 s51, s49, -1
	s_cmp_eq_u32 s73, 12
	s_cselect_b32 s53, s27, s51
	s_cselect_b32 s52, s69, s50
	s_cselect_b32 s51, s25, s72
	s_cselect_b32 s50, s70, s71
	v_lshl_add_u64 v[148:149], s[48:49], 0, v[140:141]
	s_add_i32 m0, s57, 0xc000
	ds_read_b128 v[192:195], v157
	ds_read_b128 v[196:199], v157 offset:1024
	ds_read_b128 v[200:203], v157 offset:2048
	ds_read_b128 v[204:207], v157 offset:3072
	ds_read_b128 v[208:211], v157 offset:4096
	ds_read_b128 v[212:215], v157 offset:5120
	ds_read_b128 v[216:219], v157 offset:6144
	ds_read_b128 v[220:223], v157 offset:7168
	global_load_lds_dwordx4 v[148:149], off
	v_lshl_add_u64 v[148:149], s[48:49], 0, v[142:143]
	s_add_i32 m0, s57, 0xe000
	s_nop 0
	global_load_lds_dwordx4 v[148:149], off
	s_waitcnt vmcnt(8)
	s_waitcnt lgkmcnt(0)
	s_setprio 1
	s_barrier
	v_mfma_f32_16x16x32_bf16 v[118:121], v[160:163], v[192:195], v[118:121]
	v_mfma_f32_16x16x32_bf16 v[114:117], v[168:171], v[192:195], v[114:117]
	v_mfma_f32_16x16x32_bf16 v[106:109], v[160:163], v[200:203], v[106:109]
	v_mfma_f32_16x16x32_bf16 v[98:101], v[168:171], v[200:203], v[98:101]
	v_mfma_f32_16x16x32_bf16 v[90:93], v[160:163], v[208:211], v[90:93]
	v_mfma_f32_16x16x32_bf16 v[82:85], v[168:171], v[208:211], v[82:85]
	v_mfma_f32_16x16x32_bf16 v[74:77], v[160:163], v[216:219], v[74:77]
	v_mfma_f32_16x16x32_bf16 v[66:69], v[168:171], v[216:219], v[66:69]
	v_mfma_f32_16x16x32_bf16 v[118:121], v[164:167], v[196:199], v[118:121]
	v_mfma_f32_16x16x32_bf16 v[114:117], v[172:175], v[196:199], v[114:117]
	v_mfma_f32_16x16x32_bf16 v[106:109], v[164:167], v[204:207], v[106:109]
	v_mfma_f32_16x16x32_bf16 v[98:101], v[172:175], v[204:207], v[98:101]
	v_mfma_f32_16x16x32_bf16 v[90:93], v[164:167], v[212:215], v[90:93]
	v_mfma_f32_16x16x32_bf16 v[82:85], v[172:175], v[212:215], v[82:85]
	v_mfma_f32_16x16x32_bf16 v[74:77], v[164:167], v[220:223], v[74:77]
	v_mfma_f32_16x16x32_bf16 v[66:69], v[172:175], v[220:223], v[66:69]
	s_setprio 0
	s_setprio 1
	v_mfma_f32_16x16x32_bf16 v[126:129], v[176:179], v[192:195], v[126:129]
	v_mfma_f32_16x16x32_bf16 v[122:125], v[184:187], v[192:195], v[122:125]
	v_mfma_f32_16x16x32_bf16 v[110:113], v[176:179], v[200:203], v[110:113]
	v_mfma_f32_16x16x32_bf16 v[102:105], v[184:187], v[200:203], v[102:105]
	v_mfma_f32_16x16x32_bf16 v[94:97], v[176:179], v[208:211], v[94:97]
	v_mfma_f32_16x16x32_bf16 v[86:89], v[184:187], v[208:211], v[86:89]
	v_mfma_f32_16x16x32_bf16 v[78:81], v[176:179], v[216:219], v[78:81]
	v_mfma_f32_16x16x32_bf16 v[70:73], v[184:187], v[216:219], v[70:73]
	v_mfma_f32_16x16x32_bf16 v[126:129], v[180:183], v[196:199], v[126:129]
	v_mfma_f32_16x16x32_bf16 v[122:125], v[188:191], v[196:199], v[122:125]
	v_mfma_f32_16x16x32_bf16 v[110:113], v[180:183], v[204:207], v[110:113]
	v_mfma_f32_16x16x32_bf16 v[102:105], v[188:191], v[204:207], v[102:105]
	v_mfma_f32_16x16x32_bf16 v[94:97], v[180:183], v[212:215], v[94:97]
	v_mfma_f32_16x16x32_bf16 v[86:89], v[188:191], v[212:215], v[86:89]
	v_mfma_f32_16x16x32_bf16 v[78:81], v[180:183], v[220:223], v[78:81]
	v_mfma_f32_16x16x32_bf16 v[70:73], v[188:191], v[220:223], v[70:73]
	s_setprio 0
	s_add_i32 s74, s66, s54
	v_lshl_add_u64 v[148:149], s[50:51], 0, v[134:135]
	s_mov_b32 m0, s74
	ds_read_b128 v[192:195], v157 offset:16384
	ds_read_b128 v[196:199], v157 offset:17408
	ds_read_b128 v[200:203], v157 offset:18432
	ds_read_b128 v[204:207], v157 offset:19456
	ds_read_b128 v[208:211], v157 offset:20480
	ds_read_b128 v[212:215], v157 offset:21504
	ds_read_b128 v[216:219], v157 offset:22528
	ds_read_b128 v[220:223], v157 offset:23552
	global_load_lds_dwordx4 v[148:149], off
	s_add_i32 m0, s74, 0x2000
	s_add_u32 s74, s50, 0x40000
	v_lshl_add_u64 v[224:225], s[50:51], 0, v[130:131]
	s_addc_u32 s75, s51, 0
	s_add_i32 s76, s67, s54
	global_load_lds_dwordx4 v[224:225], off
	v_lshl_add_u64 v[226:227], s[74:75], 0, v[134:135]
	s_mov_b32 m0, s76
	v_lshl_add_u64 v[228:229], s[52:53], 0, v[132:133]
	global_load_lds_dwordx4 v[226:227], off
	v_lshl_add_u64 v[226:227], s[74:75], 0, v[130:131]
	s_add_i32 m0, s76, 0x2000
	s_nop 0
	global_load_lds_dwordx4 v[226:227], off
	v_lshl_add_u64 v[226:227], s[52:53], 0, v[136:137]
	s_mov_b32 m0, s57
	s_nop 0
	global_load_lds_dwordx4 v[226:227], off
	s_mov_b32 m0, s58
	s_nop 0
	global_load_lds_dwordx4 v[228:229], off
	s_waitcnt vmcnt(8)
	s_waitcnt lgkmcnt(0)
	s_setprio 1
	s_barrier
	v_mfma_f32_16x16x32_bf16 v[58:61], v[160:163], v[192:195], v[58:61]
	v_mfma_f32_16x16x32_bf16 v[50:53], v[168:171], v[192:195], v[50:53]
	v_mfma_f32_16x16x32_bf16 v[42:45], v[160:163], v[200:203], v[42:45]
	v_mfma_f32_16x16x32_bf16 v[34:37], v[168:171], v[200:203], v[34:37]
	v_mfma_f32_16x16x32_bf16 v[26:29], v[160:163], v[208:211], v[26:29]
	v_mfma_f32_16x16x32_bf16 v[18:21], v[168:171], v[208:211], v[18:21]
	v_mfma_f32_16x16x32_bf16 v[10:13], v[160:163], v[216:219], v[10:13]
	v_mfma_f32_16x16x32_bf16 v[6:9], v[168:171], v[216:219], v[6:9]
	v_mfma_f32_16x16x32_bf16 v[58:61], v[164:167], v[196:199], v[58:61]
	v_mfma_f32_16x16x32_bf16 v[50:53], v[172:175], v[196:199], v[50:53]
	v_mfma_f32_16x16x32_bf16 v[42:45], v[164:167], v[204:207], v[42:45]
	v_mfma_f32_16x16x32_bf16 v[34:37], v[172:175], v[204:207], v[34:37]
	v_mfma_f32_16x16x32_bf16 v[26:29], v[164:167], v[212:215], v[26:29]
	v_mfma_f32_16x16x32_bf16 v[18:21], v[172:175], v[212:215], v[18:21]
	v_mfma_f32_16x16x32_bf16 v[10:13], v[164:167], v[220:223], v[10:13]
	v_mfma_f32_16x16x32_bf16 v[6:9], v[172:175], v[220:223], v[6:9]
	s_setprio 0
	s_setprio 1
	v_mfma_f32_16x16x32_bf16 v[62:65], v[176:179], v[192:195], v[62:65]
	v_mfma_f32_16x16x32_bf16 v[54:57], v[184:187], v[192:195], v[54:57]
	v_mfma_f32_16x16x32_bf16 v[46:49], v[176:179], v[200:203], v[46:49]
	v_mfma_f32_16x16x32_bf16 v[38:41], v[184:187], v[200:203], v[38:41]
	v_mfma_f32_16x16x32_bf16 v[30:33], v[176:179], v[208:211], v[30:33]
	v_mfma_f32_16x16x32_bf16 v[22:25], v[184:187], v[208:211], v[22:25]
	v_mfma_f32_16x16x32_bf16 v[14:17], v[176:179], v[216:219], v[14:17]
	v_mfma_f32_16x16x32_bf16 v[2:5], v[184:187], v[216:219], v[2:5]
	v_mfma_f32_16x16x32_bf16 v[62:65], v[180:183], v[196:199], v[62:65]
	v_mfma_f32_16x16x32_bf16 v[54:57], v[188:191], v[196:199], v[54:57]
	v_mfma_f32_16x16x32_bf16 v[46:49], v[180:183], v[204:207], v[46:49]
	v_mfma_f32_16x16x32_bf16 v[38:41], v[188:191], v[204:207], v[38:41]
	v_mfma_f32_16x16x32_bf16 v[30:33], v[180:183], v[212:215], v[30:33]
	v_mfma_f32_16x16x32_bf16 v[22:25], v[188:191], v[212:215], v[22:25]
	v_mfma_f32_16x16x32_bf16 v[14:17], v[180:183], v[220:223], v[14:17]
	v_mfma_f32_16x16x32_bf16 v[2:5], v[188:191], v[220:223], v[2:5]
	s_setprio 0
	s_add_i32 s74, 0, 0x18000
	v_add_u32_e32 v159, s74, v151
	s_add_i32 s75, 0, 0x1c000
	ds_read_b128 v[160:163], v159
	ds_read_b128 v[164:167], v159 offset:1024
	ds_read_b128 v[168:171], v159 offset:2048
	ds_read_b128 v[172:175], v159 offset:3072
	v_add_u32_e32 v159, s75, v151
	ds_read_b128 v[176:179], v159
	ds_read_b128 v[180:183], v159 offset:1024
	ds_read_b128 v[184:187], v159 offset:2048
	ds_read_b128 v[188:191], v159 offset:3072
	s_add_u32 s52, s52, 0x40000
	s_addc_u32 s53, s53, 0
	s_mov_b32 m0, s59
	v_lshl_add_u64 v[230:231], s[52:53], 0, v[136:137]
	ds_read_b128 v[192:195], v157 offset:32768
	ds_read_b128 v[196:199], v157 offset:33792
	ds_read_b128 v[200:203], v157 offset:34816
	ds_read_b128 v[204:207], v157 offset:35840
	ds_read_b128 v[208:211], v157 offset:36864
	ds_read_b128 v[212:215], v157 offset:37888
	ds_read_b128 v[216:219], v157 offset:38912
	ds_read_b128 v[220:223], v157 offset:39936
	global_load_lds_dwordx4 v[230:231], off
	v_lshl_add_u64 v[230:231], s[52:53], 0, v[132:133]
	s_mov_b32 m0, s60
	s_nop 0
	global_load_lds_dwordx4 v[230:231], off
	s_waitcnt vmcnt(8)
	s_waitcnt lgkmcnt(0)
	s_setprio 1
	s_barrier
	v_mfma_f32_16x16x32_bf16 v[118:121], v[160:163], v[192:195], v[118:121]
	v_mfma_f32_16x16x32_bf16 v[114:117], v[168:171], v[192:195], v[114:117]
	v_mfma_f32_16x16x32_bf16 v[106:109], v[160:163], v[200:203], v[106:109]
	v_mfma_f32_16x16x32_bf16 v[98:101], v[168:171], v[200:203], v[98:101]
	v_mfma_f32_16x16x32_bf16 v[90:93], v[160:163], v[208:211], v[90:93]
	v_mfma_f32_16x16x32_bf16 v[82:85], v[168:171], v[208:211], v[82:85]
	v_mfma_f32_16x16x32_bf16 v[74:77], v[160:163], v[216:219], v[74:77]
	v_mfma_f32_16x16x32_bf16 v[66:69], v[168:171], v[216:219], v[66:69]
	v_mfma_f32_16x16x32_bf16 v[118:121], v[164:167], v[196:199], v[118:121]
	v_mfma_f32_16x16x32_bf16 v[114:117], v[172:175], v[196:199], v[114:117]
	v_mfma_f32_16x16x32_bf16 v[106:109], v[164:167], v[204:207], v[106:109]
	v_mfma_f32_16x16x32_bf16 v[98:101], v[172:175], v[204:207], v[98:101]
	v_mfma_f32_16x16x32_bf16 v[90:93], v[164:167], v[212:215], v[90:93]
	v_mfma_f32_16x16x32_bf16 v[82:85], v[172:175], v[212:215], v[82:85]
	v_mfma_f32_16x16x32_bf16 v[74:77], v[164:167], v[220:223], v[74:77]
	v_mfma_f32_16x16x32_bf16 v[66:69], v[172:175], v[220:223], v[66:69]
	s_setprio 0
	s_setprio 1
	v_mfma_f32_16x16x32_bf16 v[126:129], v[176:179], v[192:195], v[126:129]
	v_mfma_f32_16x16x32_bf16 v[122:125], v[184:187], v[192:195], v[122:125]
	v_mfma_f32_16x16x32_bf16 v[110:113], v[176:179], v[200:203], v[110:113]
	v_mfma_f32_16x16x32_bf16 v[102:105], v[184:187], v[200:203], v[102:105]
	v_mfma_f32_16x16x32_bf16 v[94:97], v[176:179], v[208:211], v[94:97]
	v_mfma_f32_16x16x32_bf16 v[86:89], v[184:187], v[208:211], v[86:89]
	v_mfma_f32_16x16x32_bf16 v[78:81], v[176:179], v[216:219], v[78:81]
	v_mfma_f32_16x16x32_bf16 v[70:73], v[184:187], v[216:219], v[70:73]
	v_mfma_f32_16x16x32_bf16 v[126:129], v[180:183], v[196:199], v[126:129]
	v_mfma_f32_16x16x32_bf16 v[122:125], v[188:191], v[196:199], v[122:125]
	v_mfma_f32_16x16x32_bf16 v[110:113], v[180:183], v[204:207], v[110:113]
	v_mfma_f32_16x16x32_bf16 v[102:105], v[188:191], v[204:207], v[102:105]
	v_mfma_f32_16x16x32_bf16 v[94:97], v[180:183], v[212:215], v[94:97]
	v_mfma_f32_16x16x32_bf16 v[86:89], v[188:191], v[212:215], v[86:89]
	v_mfma_f32_16x16x32_bf16 v[78:81], v[180:183], v[220:223], v[78:81]
	v_mfma_f32_16x16x32_bf16 v[70:73], v[188:191], v[220:223], v[70:73]
	s_setprio 0
	s_add_i32 s52, s74, s54
	v_lshl_add_u64 v[148:149], v[148:149], 0, s[14:15]
	s_mov_b32 m0, s52
	ds_read_b128 v[192:195], v157 offset:49152
	ds_read_b128 v[196:199], v157 offset:50176
	ds_read_b128 v[200:203], v157 offset:51200
	ds_read_b128 v[204:207], v157 offset:52224
	ds_read_b128 v[208:211], v157 offset:53248
	ds_read_b128 v[212:215], v157 offset:54272
	ds_read_b128 v[216:219], v157 offset:55296
	ds_read_b128 v[220:223], v157 offset:56320
	global_load_lds_dwordx4 v[148:149], off
	s_add_i32 m0, s52, 0x2000
	s_add_u32 s50, s50, 0x40080
	v_lshl_add_u64 v[148:149], v[224:225], 0, s[14:15]
	s_addc_u32 s51, s51, 0
	s_add_i32 s52, s75, s54
	global_load_lds_dwordx4 v[148:149], off
	v_lshl_add_u64 v[148:149], s[50:51], 0, v[134:135]
	s_mov_b32 m0, s52
	s_nop 0
	global_load_lds_dwordx4 v[148:149], off
	v_lshl_add_u64 v[148:149], s[50:51], 0, v[130:131]
	s_add_i32 m0, s52, 0x2000
	s_nop 0
	global_load_lds_dwordx4 v[148:149], off
	v_lshl_add_u64 v[148:149], v[226:227], 0, s[14:15]
	s_mov_b32 m0, s62
	s_nop 0
	global_load_lds_dwordx4 v[148:149], off
	v_lshl_add_u64 v[148:149], v[228:229], 0, s[14:15]
	s_mov_b32 m0, s63
	s_nop 0
	global_load_lds_dwordx4 v[148:149], off
	s_waitcnt vmcnt(8)
	s_waitcnt lgkmcnt(0)
	s_setprio 1
	s_barrier
	v_mfma_f32_16x16x32_bf16 v[58:61], v[160:163], v[192:195], v[58:61]
	v_mfma_f32_16x16x32_bf16 v[50:53], v[168:171], v[192:195], v[50:53]
	v_mfma_f32_16x16x32_bf16 v[42:45], v[160:163], v[200:203], v[42:45]
	v_mfma_f32_16x16x32_bf16 v[34:37], v[168:171], v[200:203], v[34:37]
	v_mfma_f32_16x16x32_bf16 v[26:29], v[160:163], v[208:211], v[26:29]
	v_mfma_f32_16x16x32_bf16 v[18:21], v[168:171], v[208:211], v[18:21]
	v_mfma_f32_16x16x32_bf16 v[10:13], v[160:163], v[216:219], v[10:13]
	v_mfma_f32_16x16x32_bf16 v[6:9], v[168:171], v[216:219], v[6:9]
	v_mfma_f32_16x16x32_bf16 v[58:61], v[164:167], v[196:199], v[58:61]
	v_mfma_f32_16x16x32_bf16 v[50:53], v[172:175], v[196:199], v[50:53]
	v_mfma_f32_16x16x32_bf16 v[42:45], v[164:167], v[204:207], v[42:45]
	v_mfma_f32_16x16x32_bf16 v[34:37], v[172:175], v[204:207], v[34:37]
	v_mfma_f32_16x16x32_bf16 v[26:29], v[164:167], v[212:215], v[26:29]
	v_mfma_f32_16x16x32_bf16 v[18:21], v[172:175], v[212:215], v[18:21]
	v_mfma_f32_16x16x32_bf16 v[10:13], v[164:167], v[220:223], v[10:13]
	v_mfma_f32_16x16x32_bf16 v[6:9], v[172:175], v[220:223], v[6:9]
	s_setprio 0
	s_setprio 1
	v_mfma_f32_16x16x32_bf16 v[62:65], v[176:179], v[192:195], v[62:65]
	v_mfma_f32_16x16x32_bf16 v[54:57], v[184:187], v[192:195], v[54:57]
	v_mfma_f32_16x16x32_bf16 v[46:49], v[176:179], v[200:203], v[46:49]
	v_mfma_f32_16x16x32_bf16 v[38:41], v[184:187], v[200:203], v[38:41]
	v_mfma_f32_16x16x32_bf16 v[30:33], v[176:179], v[208:211], v[30:33]
	v_mfma_f32_16x16x32_bf16 v[22:25], v[184:187], v[208:211], v[22:25]
	v_mfma_f32_16x16x32_bf16 v[14:17], v[176:179], v[216:219], v[14:17]
	v_mfma_f32_16x16x32_bf16 v[2:5], v[184:187], v[216:219], v[2:5]
	v_mfma_f32_16x16x32_bf16 v[62:65], v[180:183], v[196:199], v[62:65]
	v_mfma_f32_16x16x32_bf16 v[54:57], v[188:191], v[196:199], v[54:57]
	v_mfma_f32_16x16x32_bf16 v[46:49], v[180:183], v[204:207], v[46:49]
	v_mfma_f32_16x16x32_bf16 v[38:41], v[188:191], v[204:207], v[38:41]
	v_mfma_f32_16x16x32_bf16 v[30:33], v[180:183], v[212:215], v[30:33]
	v_mfma_f32_16x16x32_bf16 v[22:25], v[188:191], v[212:215], v[22:25]
	v_mfma_f32_16x16x32_bf16 v[14:17], v[180:183], v[220:223], v[14:17]
	v_mfma_f32_16x16x32_bf16 v[2:5], v[188:191], v[220:223], v[2:5]
	s_setprio 0
	s_add_i32 s73, s73, 2
	s_add_u32 s48, s48, 0x100
	s_addc_u32 s49, s49, 0
	s_add_u32 s71, s71, 0x100
	s_addc_u32 s72, s72, 0
	s_cmp_gt_u32 s73, 13
	s_cbranch_scc0 .Lhb_B_p1
